# RNN tile loop: kb0 LDS reads hoisted to tile top + y-gather overlapped with conv MFMAs; g-load issued before y-store so vmcnt waits no longer cover the previous y store
# speedup vs baseline: 1.0069x; 1.0069x over previous
.LBB0_109:
	s_or_b64 exec, exec, s[10:11]
	s_lshl_b64 s[20:21], s[0:1], 12
	s_add_u32 s0, s16, s20
	s_addc_u32 s1, s17, s21
	s_add_u32 s0, s0, s6
	s_addc_u32 s1, s1, 0
	s_add_u32 s0, s0, s7
	v_ashrrev_i32_e32 v0, 6, v182
	s_addc_u32 s1, s1, 0
	v_mov_b32_e32 v171, v1
	v_lshlrev_b32_e32 v148, 1, v168
	v_lshl_or_b32 v142, v0, 2, v213
	v_lshl_add_u64 v[146:147], s[0:1], 0, v[170:171]
	v_lshl_add_u64 v[2:3], s[26:27], 0, v[170:171]
	v_add_u32_e32 v171, s52, v148
	v_lshlrev_b32_e32 v0, 4, v0
	s_movk_i32 s6, 0x420
	v_add3_u32 v143, v213, v141, v0
	v_or_b32_e32 v220, v0, v141
	v_lshl_add_u32 v224, v141, 6, s98
	v_mul_lo_u32 v225, v142, s6
	v_mul_lo_u32 v142, v142, s51
	v_lshlrev_b32_e32 v0, 4, v141
	v_mad_u32_u24 v141, v183, s51, v171
	v_mul_lo_u32 v150, v143, s51
	v_add_u32_e32 v226, s99, v142
	v_add_u32_e32 v227, s52, v142
	ds_read_u16 v142, v141
	ds_read_u16 v151, v141 offset:272
	ds_read_u16 v143, v141 offset:544
	ds_read_u16 v153, v141 offset:816
	ds_read_u16 v144, v141 offset:1088
	ds_read_u16 v155, v141 offset:1360
	ds_read_u16 v145, v141 offset:1632
	ds_read_u16 v141, v141 offset:1904
	v_lshlrev_b64 v[184:185], 12, v[168:169]
	v_mad_u32_u24 v152, v183, s51, v252
	s_waitcnt lgkmcnt(4)
	v_perm_b32 v143, v153, v143, s8
	s_waitcnt lgkmcnt(2)
	v_perm_b32 v144, v155, v144, s8
	s_waitcnt lgkmcnt(0)
	v_perm_b32 v145, v141, v145, s8
	v_mov_b32_e32 v141, s99
	v_mad_u32_u24 v141, v183, s51, v141
	v_perm_b32 v142, v151, v142, s8
	v_lshl_add_u64 v[146:147], v[146:147], 0, v[184:185]
	v_add_u32_e32 v175, v141, v148
	global_store_dwordx4 v[146:147], v[142:145], off
	ds_write_b16 v175, v120
	ds_write_b16_d16_hi v175, v120 offset:272
	v_add_u32_e32 v120, s99, v152
	v_add_u32_e32 v200, s99, v148
	v_mad_u32_u24 v154, v183, s51, v194
	v_add_u32_e32 v141, v200, v152
	v_add_u32_e32 v201, v120, v148
	v_mad_u32_u24 v156, v183, s51, v195
	ds_write_b16 v141, v121
	ds_write_b16_d16_hi v201, v121 offset:272
	v_add_u32_e32 v120, s99, v154
	v_add_u32_e32 v121, v200, v154
	ds_write_b16 v121, v122
	v_add_u32_e32 v202, v120, v148
	v_add_u32_e32 v120, s99, v156
	v_add_u32_e32 v121, v200, v156
	v_and_b32_e32 v149, 48, v182
	ds_write_b16 v121, v123
	v_add_u32_e32 v203, v120, v148
	v_lshlrev_b64 v[120:121], 11, v[168:169]
	v_lshl_add_u64 v[120:121], v[2:3], 0, v[120:121]
	s_mov_b32 s6, 0x40000
	v_add_u32_e32 v141, 0, v149
	ds_write_b16_d16_hi v202, v122 offset:272
	ds_write_b16_d16_hi v203, v123 offset:272
	v_add_co_u32_e32 v120, vcc, s6, v120
	v_add_u32_e32 v204, 0x19c00, v141
	s_nop 0
	v_addc_co_u32_e32 v121, vcc, 0, v121, vcc
	ds_read_b128 v[142:145], v204
	global_load_dwordx4 v[120:123], v[120:121], off
	v_add_u32_e32 v205, 0, v150
	ds_read_b128 v[146:149], v204 offset:64
	ds_read_b128 v[150:153], v205
	ds_read_b128 v[154:157], v205 offset:16
	ds_read_b128 v[158:161], v205 offset:32
	ds_read_b128 v[162:165], v205 offset:48
	s_waitcnt lgkmcnt(3)
	v_mfma_f32_16x16x32_bf16 v[142:145], v[4:7], v[150:153], v[142:145]
	s_cmp_eq_u32 s28, 0
	s_cselect_b64 vcc, -1, 0
	s_cmp_eq_u32 s28, 1
	s_waitcnt lgkmcnt(1)
	v_mfma_f32_16x16x32_bf16 v[146:149], v[12:15], v[158:161], v[146:149]
	s_cselect_b64 s[40:41], -1, 0
	s_cmp_eq_u32 s28, 2
	s_cselect_b64 s[42:43], -1, 0
	v_mfma_f32_16x16x32_bf16 v[142:145], v[8:11], v[154:157], v[142:145]
	s_cmp_eq_u32 s28, 3
	s_cselect_b64 s[44:45], -1, 0
	s_add_i32 s6, 0, 0x19800
	s_waitcnt lgkmcnt(0)
	v_mfma_f32_16x16x32_bf16 v[146:149], v[16:19], v[162:165], v[146:149]
	v_add_u32_e32 v224, v224, v225
	s_nop 1
	v_cvt_pk_bf16_f32 v142, v142, v143
	v_cvt_pk_bf16_f32 v143, v144, v145
	v_cndmask_b32_e32 v167, 0, v142, vcc
	v_cndmask_b32_e32 v190, 0, v143, vcc
	s_nop 0
	v_cvt_pk_bf16_f32 v144, v146, v147
	v_cvt_pk_bf16_f32 v145, v148, v149
	v_cndmask_b32_e32 v141, 0, v144, vcc
	v_cndmask_b32_e32 v166, 0, v145, vcc
	v_mfma_f32_16x16x32_bf16 v[146:149], v[52:55], v[142:145], 0
	v_add_u32_e32 v226, v226, v0
	v_add_u32_e32 v227, v227, v0
	v_mfma_f32_16x16x32_bf16 v[150:153], v[68:71], v[142:145], 0
	v_mfma_f32_16x16x32_bf16 v[154:157], v[84:87], v[142:145], 0
	v_mfma_f32_16x16x32_bf16 v[158:161], v[100:103], v[142:145], 0
	ds_read_b128 v[142:145], v204 offset:128
	ds_read_b128 v[162:165], v205 offset:64
	ds_read_b128 v[206:209], v205 offset:80
	ds_read_b128 v[228:231], v204 offset:192
	ds_read_b128 v[238:241], v205 offset:96
	ds_read_b128 v[242:245], v205 offset:112
	s_waitcnt lgkmcnt(4)
	v_mfma_f32_16x16x32_bf16 v[142:145], v[20:23], v[162:165], v[142:145]
	s_waitcnt lgkmcnt(1)
	v_mfma_f32_16x16x32_bf16 v[162:165], v[28:31], v[238:241], v[228:231]
	v_mfma_f32_16x16x32_bf16 v[142:145], v[24:27], v[206:209], v[142:145]
	s_waitcnt lgkmcnt(0)
	v_mfma_f32_16x16x32_bf16 v[162:165], v[32:35], v[242:245], v[162:165]
	s_nop 5
	v_cvt_pk_bf16_f32 v142, v142, v143
	v_cvt_pk_bf16_f32 v143, v144, v145
	v_cvt_pk_bf16_f32 v144, v162, v163
	v_cvt_pk_bf16_f32 v145, v164, v165
	v_cndmask_b32_e64 v166, v166, v145, s[40:41]
	v_cndmask_b32_e64 v141, v141, v144, s[40:41]
	v_mfma_f32_16x16x32_bf16 v[146:149], v[56:59], v[142:145], v[146:149]
	v_cndmask_b32_e64 v190, v190, v143, s[40:41]
	v_cndmask_b32_e64 v167, v167, v142, s[40:41]
	v_mfma_f32_16x16x32_bf16 v[150:153], v[72:75], v[142:145], v[150:153]
	v_mfma_f32_16x16x32_bf16 v[154:157], v[88:91], v[142:145], v[154:157]
	v_mfma_f32_16x16x32_bf16 v[158:161], v[104:107], v[142:145], v[158:161]
	ds_read_b128 v[142:145], v204 offset:256
	ds_read_b128 v[162:165], v205 offset:128
	ds_read_b128 v[206:209], v205 offset:144
	ds_read_b128 v[228:231], v204 offset:320
	ds_read_b128 v[238:241], v205 offset:160
	ds_read_b128 v[242:245], v205 offset:176
	s_waitcnt lgkmcnt(4)
	v_mfma_f32_16x16x32_bf16 v[142:145], v[36:39], v[162:165], v[142:145]
	s_waitcnt lgkmcnt(1)
	v_mfma_f32_16x16x32_bf16 v[162:165], v[44:47], v[238:241], v[228:231]
	v_mfma_f32_16x16x32_bf16 v[142:145], v[40:43], v[206:209], v[142:145]
	v_add_u32_e32 v206, 0x21a00, v140
	v_add_u32_e32 v207, 0x22200, v140
	s_waitcnt lgkmcnt(0)
	v_mfma_f32_16x16x32_bf16 v[162:165], v[48:51], v[242:245], v[162:165]
	s_nop 3
	v_cvt_pk_bf16_f32 v142, v142, v143
	v_cvt_pk_bf16_f32 v143, v144, v145
	s_nop 1
	v_cvt_pk_bf16_f32 v144, v162, v163
	v_cvt_pk_bf16_f32 v145, v164, v165
	v_cndmask_b32_e64 v141, v141, v144, s[42:43]
	v_cndmask_b32_e64 v166, v166, v145, s[42:43]
	v_mfma_f32_16x16x32_bf16 v[146:149], v[60:63], v[142:145], v[146:149]
	v_mfma_f32_16x16x32_bf16 v[162:165], v[76:79], v[142:145], v[150:153]
	v_mfma_f32_16x16x32_bf16 v[228:231], v[92:95], v[142:145], v[154:157]
	v_mfma_f32_16x16x32_bf16 v[156:159], v[108:111], v[142:145], v[158:161]
	s_nop 2
	v_cndmask_b32_e64 v160, v167, v142, s[42:43]
	v_cndmask_b32_e64 v161, v190, v143, s[42:43]
	ds_read_b128 v[142:145], v204 offset:384
	ds_read_b128 v[150:153], v205 offset:192
	ds_read_b128 v[238:241], v205 offset:208
	ds_read_b128 v[208:211], v204 offset:448
	ds_read_b128 v[242:245], v205 offset:224
	ds_read_b128 v[246:249], v205 offset:240
	ds_read_b128 v[190:193], v206
	s_waitcnt lgkmcnt(0)
	v_mfma_f32_16x16x32_bf16 v[142:145], v[190:193], v[150:153], v[142:145]
	ds_read_b128 v[150:153], v207
	s_waitcnt lgkmcnt(0)
	v_mfma_f32_16x16x32_bf16 v[150:153], v[150:153], v[242:245], v[208:211]
	s_nop 2
	v_add_u32_e32 v208, 0x21e00, v140
	ds_read_b128 v[190:193], v208
	v_add_u32_e32 v209, 0x22600, v140
	s_waitcnt lgkmcnt(0)
	v_mfma_f32_16x16x32_bf16 v[142:145], v[190:193], v[238:241], v[142:145]
	ds_read_b128 v[190:193], v209
	s_waitcnt lgkmcnt(0)
	v_mfma_f32_16x16x32_bf16 v[150:153], v[190:193], v[246:249], v[150:153]
	s_nop 4
	v_cvt_pk_bf16_f32 v190, v142, v143
	v_cvt_pk_bf16_f32 v191, v144, v145
	s_nop 0
	v_cvt_pk_bf16_f32 v192, v150, v151
	v_cvt_pk_bf16_f32 v193, v152, v153
	v_cndmask_b32_e64 v219, v141, v192, s[44:45]
	v_cndmask_b32_e64 v218, v166, v193, s[44:45]
	v_mfma_f32_16x16x32_bf16 v[140:143], v[112:115], v[190:193], v[156:159]
	s_nop 2
	v_cndmask_b32_e64 v156, v161, v191, s[44:45]
	v_lshlrev_b32_e32 v215, 16, v156
	v_and_b32_e32 v216, 0xffff0000, v156
	v_lshlrev_b32_e32 v156, 2, v217
	v_add_u32_e32 v210, s6, v156
	v_mfma_f32_16x16x32_bf16 v[152:155], v[64:67], v[190:193], v[146:149]
	v_add_u32_e32 v211, s53, v156
	v_cndmask_b32_e64 v157, v160, v190, s[44:45]
	v_add_u32_e32 v212, s54, v156
	v_mfma_f32_16x16x32_bf16 v[144:147], v[80:83], v[190:193], v[162:165]
	v_lshlrev_b32_e32 v221, 16, v157
	v_and_b32_e32 v214, 0xffff0000, v157
	ds_read_b128 v[156:159], v212
	ds_read_b128 v[164:167], v210
	ds_read_b128 v[160:163], v211
	v_mfma_f32_16x16x32_bf16 v[148:151], v[96:99], v[190:193], v[228:231]
	s_waitcnt lgkmcnt(1)
	v_add_f32_e32 v152, v152, v164
	v_exp_f32_e32 v152, v152
	v_and_b32_e32 v164, 0xffff0000, v219
	s_waitcnt lgkmcnt(0)
	s_nop 2
	v_add_f32_e32 v148, v148, v160
	v_exp_f32_e32 v148, v148
	v_add_f32_e32 v152, 1.0, v152
	v_rcp_f32_e64 v152, -v152
	v_add_f32_e32 v149, v149, v161
	v_add_f32_e32 v148, 1.0, v148
	v_rcp_f32_e32 v148, v148
	v_mul_f32_e32 v152, v156, v152
	v_exp_f32_e32 v190, v152
	v_exp_f32_e32 v149, v149
	v_mul_f32_e32 v148, v148, v221
	v_or_b32_e32 v161, 16, v217
	v_fma_f32 v152, -v190, v190, 1.0
	v_max_f32_e32 v152, 0, v152
	v_sqrt_f32_e32 v152, v152
	v_add_f32_e32 v149, 1.0, v149
	v_rcp_f32_e32 v149, v149
	v_mul_f32_e32 v191, v148, v152
	v_mul_u32_u24_e32 v148, 0x210, v213
	v_add_lshl_u32 v160, v220, v148, 3
	v_add_f32_e32 v148, v153, v165
	v_exp_f32_e32 v148, v148
	v_mul_f32_e32 v149, v149, v214
	v_add_u32_e32 v213, s98, v160
	ds_write_b64 v213, v[190:191]
	v_add_f32_e32 v148, 1.0, v148
	v_rcp_f32_e64 v148, -v148
	v_lshlrev_b32_e32 v165, 16, v218
	v_mul_f32_e32 v148, v157, v148
	v_exp_f32_e32 v148, v148
	s_nop 0
	v_fma_f32 v152, -v148, v148, 1.0
	v_max_f32_e32 v152, 0, v152
	v_sqrt_f32_e32 v152, v152
	s_nop 0
	v_mul_f32_e32 v149, v149, v152
	v_add_u32_e32 v152, 0x420, v160
	v_add_u32_e32 v214, s98, v152
	ds_write_b64 v214, v[148:149]
	v_add_f32_e32 v148, v154, v166
	v_exp_f32_e32 v148, v148
	v_add_f32_e32 v149, v150, v162
	v_exp_f32_e32 v149, v149
	v_and_b32_e32 v166, 0xffff0000, v218
	v_add_f32_e32 v148, 1.0, v148
	v_rcp_f32_e64 v148, -v148
	v_add_f32_e32 v149, 1.0, v149
	v_rcp_f32_e32 v149, v149
	v_mul_f32_e32 v148, v158, v148
	v_exp_f32_e32 v148, v148
	v_mul_f32_e32 v149, v149, v215
	v_fma_f32 v150, -v148, v148, 1.0
	v_max_f32_e32 v150, 0, v150
	v_sqrt_f32_e32 v150, v150
	s_nop 0
	v_mul_f32_e32 v149, v149, v150
	v_add_u32_e32 v150, 0x840, v160
	v_add_u32_e32 v215, s98, v150
	ds_write_b64 v215, v[148:149]
	v_add_f32_e32 v148, v155, v167
	v_exp_f32_e32 v148, v148
	v_add_f32_e32 v149, v151, v163
	v_exp_f32_e32 v149, v149
	v_lshlrev_b32_e32 v163, 16, v219
	v_add_f32_e32 v148, 1.0, v148
	v_rcp_f32_e64 v148, -v148
	v_add_f32_e32 v149, 1.0, v149
	v_rcp_f32_e32 v149, v149
	v_mul_f32_e32 v148, v159, v148
	v_exp_f32_e32 v148, v148
	v_mul_f32_e32 v149, v149, v216
	v_fma_f32 v150, -v148, v148, 1.0
	v_max_f32_e32 v150, 0, v150
	v_sqrt_f32_e32 v150, v150
	s_nop 0
	v_mul_f32_e32 v149, v149, v150
	v_add_u32_e32 v150, 0xc60, v160
	v_add_u32_e32 v216, s98, v150
	ds_write_b64 v216, v[148:149]
	v_lshlrev_b32_e32 v148, 2, v161
	v_add_u32_e32 v217, s6, v148
	ds_read_b128 v[156:159], v217
	v_add_u32_e32 v218, s53, v148
	ds_read_b128 v[152:155], v218
	v_add_u32_e32 v219, s54, v148
	ds_read_b128 v[148:151], v219
	s_waitcnt lgkmcnt(2)
	v_add_f32_e32 v144, v144, v156
	v_exp_f32_e32 v144, v144
	s_waitcnt lgkmcnt(1)
	v_add_f32_e32 v140, v140, v152
	v_exp_f32_e32 v140, v140
	v_add_f32_e32 v141, v141, v153
	v_add_f32_e32 v144, 1.0, v144
	v_rcp_f32_e64 v144, -v144
	v_add_f32_e32 v140, 1.0, v140
	v_rcp_f32_e32 v140, v140
	v_exp_f32_e32 v141, v141
	s_waitcnt lgkmcnt(0)
	v_mul_f32_e32 v144, v148, v144
	v_exp_f32_e32 v162, v144
	v_mul_f32_e32 v140, v140, v163
	v_add_f32_e32 v141, 1.0, v141
	v_rcp_f32_e32 v141, v141
	v_fma_f32 v144, -v162, v162, 1.0
	v_max_f32_e32 v144, 0, v144
	v_sqrt_f32_e32 v144, v144
	v_mul_f32_e32 v141, v141, v164
	v_mul_f32_e32 v163, v140, v144
	v_mul_u32_u24_e32 v140, 0x84, v161
	v_add_lshl_u32 v140, v140, v220, 3
	v_add_u32_e32 v220, s98, v140
	v_add_f32_e32 v140, v145, v157
	v_exp_f32_e32 v140, v140
	ds_write_b64 v220, v[162:163]
	v_mov_b32_e32 v161, v1
	v_add_f32_e32 v140, 1.0, v140
	v_rcp_f32_e64 v140, -v140
	s_nop 0
	v_mul_f32_e32 v140, v149, v140
	v_exp_f32_e32 v140, v140
	s_nop 0
	v_fma_f32 v144, -v140, v140, 1.0
	v_max_f32_e32 v144, 0, v144
	v_sqrt_f32_e32 v144, v144
	s_nop 0
	v_mul_f32_e32 v141, v141, v144
	v_add_u32_e32 v144, 0x4620, v160
	v_add_u32_e32 v221, s98, v144
	ds_write_b64 v221, v[140:141]
	v_add_f32_e32 v140, v146, v158
	v_exp_f32_e32 v140, v140
	v_add_f32_e32 v141, v142, v154
	v_exp_f32_e32 v141, v141
	v_add_f32_e32 v140, 1.0, v140
	v_rcp_f32_e64 v140, -v140
	v_add_f32_e32 v141, 1.0, v141
	v_rcp_f32_e32 v141, v141
	v_mul_f32_e32 v140, v150, v140
	v_exp_f32_e32 v140, v140
	v_mul_f32_e32 v141, v141, v165
	v_fma_f32 v142, -v140, v140, 1.0
	v_max_f32_e32 v142, 0, v142
	v_sqrt_f32_e32 v142, v142
	s_nop 0
	v_mul_f32_e32 v141, v141, v142
	v_add_u32_e32 v142, 0x4a40, v160
	v_add_u32_e32 v222, s98, v142
	ds_write_b64 v222, v[140:141]
	v_add_f32_e32 v140, v147, v159
	v_exp_f32_e32 v140, v140
	v_add_f32_e32 v141, v143, v155
	v_exp_f32_e32 v141, v141
	v_add_f32_e32 v140, 1.0, v140
	v_rcp_f32_e64 v140, -v140
	v_add_f32_e32 v141, 1.0, v141
	v_rcp_f32_e32 v141, v141
	v_mul_f32_e32 v140, v151, v140
	v_exp_f32_e32 v140, v140
	v_mul_f32_e32 v141, v141, v166
	v_fma_f32 v142, -v140, v140, 1.0
	v_max_f32_e32 v142, 0, v142
	v_sqrt_f32_e32 v142, v142
	s_nop 0
	v_mul_f32_e32 v141, v141, v142
	v_add_u32_e32 v142, 0x4e60, v160
	v_add_u32_e32 v223, s98, v142
	ds_write_b64 v223, v[140:141]
	s_waitcnt lgkmcnt(0)
	s_barrier
	ds_read_b128 v[148:151], v224
	ds_read_b128 v[152:155], v224 offset:16
	ds_read_b128 v[144:147], v224 offset:32
	ds_read_b128 v[140:143], v224 offset:48
	s_waitcnt lgkmcnt(3)
	v_fma_f32 v149, 0, v148, v149
	v_fma_f32 v156, v150, v149, v151
	v_mul_f32_e32 v157, v148, v150
	s_waitcnt lgkmcnt(2)
	v_fma_f32 v158, v152, v156, v153
	v_mul_f32_e32 v159, v157, v152
	v_mul_f32_e32 v160, v154, v159
	v_fmac_f32_e32 v155, v154, v158
	s_waitcnt lgkmcnt(1)
	v_fma_f32 v145, v144, v155, v145
	v_mul_f32_e32 v144, v144, v160
	v_mul_f32_e32 v154, v146, v144
	v_fmac_f32_e32 v147, v146, v145
	s_waitcnt lgkmcnt(0)
	v_fma_f32 v141, v140, v147, v141
	v_mul_f32_e32 v140, v140, v154
	v_mul_f32_e32 v146, v142, v140
	v_fmac_f32_e32 v143, v142, v141
	v_mov_b32_e32 v142, 1.0
	v_mov_b32_e32 v150, v1
	v_mov_b32_e32 v151, 1.0
	v_mov_b32_dpp v142, v146 row_shr:1 row_mask:0xf bank_mask:0xf
	v_mov_b32_dpp v150, v143 row_shr:1 row_mask:0xf bank_mask:0xf
	v_fma_f32 v150, v146, v150, v143
	v_mul_f32_e32 v142, v146, v142
	v_mov_b32_e32 v152, v1
	s_nop 0
	v_mov_b32_dpp v151, v142 row_shr:2 row_mask:0xf bank_mask:0xf
	v_mov_b32_dpp v152, v150 row_shr:2 row_mask:0xf bank_mask:0xf
	v_fmac_f32_e32 v150, v142, v152
	v_mul_f32_e32 v142, v142, v151
	v_mov_b32_e32 v151, 1.0
	v_mov_b32_e32 v152, v1
	s_nop 0
	v_mov_b32_dpp v151, v142 row_shr:4 row_mask:0xf bank_mask:0xf
	v_mov_b32_dpp v152, v150 row_shr:4 row_mask:0xf bank_mask:0xf
	v_fmac_f32_e32 v150, v142, v152
	v_mul_f32_e32 v142, v142, v151
	v_mov_b32_e32 v151, 1.0
	v_mov_b32_e32 v152, v1
	s_nop 0
	v_mov_b32_dpp v151, v142 row_shr:8 row_mask:0xf bank_mask:0xf
	v_mov_b32_dpp v152, v150 row_shr:8 row_mask:0xf bank_mask:0xf
	v_fmac_f32_e32 v150, v142, v152
	v_mul_f32_e32 v142, v142, v151
	v_mov_b32_e32 v151, 1.0
	v_mov_b32_dpp v161, v150 row_shr:1 row_mask:0xf bank_mask:0xf
	v_fmac_f32_e32 v150, 0, v142
	v_mov_b32_dpp v151, v142 row_shr:1 row_mask:0xf bank_mask:0xf
	v_fmac_f32_e32 v161, 0, v151
	ds_bpermute_b32 v225, v196, v150
	ds_read_b128 v[150:153], v226
	v_fmac_f32_e32 v145, v144, v161
	v_fmac_f32_e32 v149, v148, v161
	v_fmac_f32_e32 v147, v154, v161
	v_fmac_f32_e32 v141, v140, v161
	s_waitcnt lgkmcnt(0)
	v_lshlrev_b32_e32 v163, 16, v152
	v_lshlrev_b32_e32 v142, 16, v150
	v_mul_f32_e32 v144, v145, v163
	v_mul_f32_e32 v145, 0xbfb8aa3b, v163
	v_mul_f32_e32 v148, v149, v142
	v_mul_f32_e32 v142, 0xbfb8aa3b, v142
	v_exp_f32_e32 v145, v145
	v_exp_f32_e32 v142, v142
	v_and_b32_e32 v150, 0xffff0000, v150
	v_and_b32_e32 v152, 0xffff0000, v152
	v_add_f32_e32 v145, 1.0, v145
	v_add_f32_e32 v142, 1.0, v142
	v_rcp_f32_e32 v145, v145
	v_rcp_f32_e32 v142, v142
	v_lshlrev_b32_e32 v164, 16, v153
	v_lshlrev_b32_e32 v162, 16, v151
	v_fmac_f32_e32 v156, v157, v161
	v_mul_f32_e32 v149, 0xbfb8aa3b, v150
	v_mul_f32_e32 v144, v144, v145
	v_mul_f32_e32 v145, v147, v152
	v_mul_f32_e32 v147, 0xbfb8aa3b, v152
	v_mul_f32_e32 v140, v141, v164
	v_mul_f32_e32 v141, 0xbfb8aa3b, v164
	v_mul_f32_e32 v142, v148, v142
	v_mul_f32_e32 v148, v156, v150
	v_exp_f32_e32 v149, v149
	v_mul_f32_e32 v150, 0xbfb8aa3b, v162
	v_exp_f32_e32 v147, v147
	v_exp_f32_e32 v141, v141
	v_exp_f32_e32 v150, v150
	v_add_f32_e32 v149, 1.0, v149
	v_add_f32_e32 v147, 1.0, v147
	v_add_f32_e32 v141, 1.0, v141
	v_rcp_f32_e32 v149, v149
	v_add_f32_e32 v150, 1.0, v150
	v_rcp_f32_e32 v147, v147
	v_rcp_f32_e32 v141, v141
	v_rcp_f32_e32 v150, v150
	v_and_b32_e32 v153, 0xffff0000, v153
	v_fmac_f32_e32 v158, v159, v161
	v_and_b32_e32 v151, 0xffff0000, v151
	v_mul_f32_e32 v148, v148, v149
	v_mul_f32_e32 v149, v158, v162
	v_fmac_f32_e32 v155, v160, v161
	v_mul_f32_e32 v145, v145, v147
	v_mul_f32_e32 v147, v140, v141
	v_mul_f32_e32 v141, 0xbfb8aa3b, v153
	v_mul_f32_e32 v149, v149, v150
	v_mul_f32_e32 v150, v155, v151
	v_mul_f32_e32 v151, 0xbfb8aa3b, v151
	v_exp_f32_e32 v141, v141
	v_exp_f32_e32 v151, v151
	v_fmac_f32_e32 v143, v146, v161
	v_mul_f32_e32 v140, v143, v153
	v_add_f32_e32 v141, 1.0, v141
	v_add_f32_e32 v151, 1.0, v151
	v_rcp_f32_e32 v141, v141
	v_rcp_f32_e32 v151, v151
	v_mul_f32_e32 v143, v140, v141
	v_mul_f32_e32 v150, v150, v151
	v_cvt_pk_bf16_f32 v140, v142, v148
	v_cvt_pk_bf16_f32 v141, v149, v150
	v_cvt_pk_bf16_f32 v142, v144, v145
	v_cvt_pk_bf16_f32 v143, v147, v143
	ds_write_b128 v227, v[140:143]
	s_waitcnt vmcnt(5)
	ds_write_b128 v177, v[124:127] offset:816
	s_waitcnt vmcnt(4)
	ds_write_b128 v179, v[128:131] offset:816
	s_waitcnt vmcnt(3)
	ds_write_b128 v181, v[132:135] offset:816
	s_waitcnt vmcnt(2)
	ds_write_b128 v199, v[136:139] offset:816
	s_and_saveexec_b64 s[10:11], s[38:39]
	ds_write_b128 v177, v[116:119]
	s_or_b64 exec, exec, s[10:11]
	s_lshl_b32 s7, s22, 3
	s_lshl_b32 s6, s23, 8
	s_and_b32 s7, s7, 0xc0
	s_or_b32 s6, s7, s6
	s_add_u32 s6, s6, s20
	s_addc_u32 s7, 0, s21
	v_and_b32_e32 v0, 3, v182
	v_lshl_add_u64 v[124:125], s[6:7], 0, v[184:185]
	v_lshlrev_b32_e32 v0, 4, v0
	v_lshl_add_u64 v[124:125], v[124:125], 0, v[0:1]
	v_mul_u32_u24_e32 v228, 0x110, v183
	v_lshl_add_u64 v[182:183], s[16:17], 0, v[124:125]
	s_movk_i32 s20, 0x100
	s_waitcnt vmcnt(0)
	s_branch .LBB0_113

.LBB0_113:
	s_cmpk_lg_i32 s20, 0x1000
	s_cselect_b32 s6, s20, 0xf80
	v_add_u32_e32 v140, s6, v174
	v_add_u32_e32 v126, s6, v176
	v_add_u32_e32 v132, s6, v178
	v_add_u32_e32 v134, s6, v180
	v_ashrrev_i32_e32 v141, 31, v140
	v_ashrrev_i32_e32 v127, 31, v126
	v_ashrrev_i32_e32 v133, 31, v132
	v_ashrrev_i32_e32 v135, 31, v134
	v_lshlrev_b64 v[124:125], 11, v[140:141]
	v_lshlrev_b64 v[126:127], 11, v[126:127]
	v_lshlrev_b64 v[132:133], 11, v[132:133]
	v_lshlrev_b64 v[134:135], 11, v[134:135]
	s_waitcnt lgkmcnt(0)
	s_barrier
	ds_read_b128 v[140:143], v204
	ds_read_b128 v[144:147], v204 offset:64
	ds_read_b128 v[148:151], v205
	ds_read_b128 v[152:155], v205 offset:16
	ds_read_b128 v[156:159], v205 offset:32
	ds_read_b128 v[160:163], v205 offset:48
	v_lshl_add_u64 v[124:125], v[172:173], 0, v[124:125]
	v_lshl_add_u64 v[128:129], v[172:173], 0, v[126:127]
	v_lshl_add_u64 v[132:133], v[172:173], 0, v[132:133]
	v_lshl_add_u64 v[136:137], v[172:173], 0, v[134:135]
	global_load_dwordx4 v[124:127], v[124:125], off
	s_nop 0
	global_load_dwordx4 v[128:131], v[128:129], off
	s_nop 0
	global_load_dwordx4 v[132:135], v[132:133], off
	s_nop 0
	global_load_dwordx4 v[136:139], v[136:137], off
	s_and_saveexec_b64 s[10:11], s[38:39]
	s_cbranch_execz .LBB0_115
	v_add3_u32 v116, v174, s6, -3
	v_ashrrev_i32_e32 v117, 31, v116
	v_lshlrev_b64 v[116:117], 11, v[116:117]
	v_lshl_add_u64 v[116:117], v[172:173], 0, v[116:117]
	global_load_dwordx4 v[116:119], v[116:117], off
.LBB0_115:
	s_or_b64 exec, exec, s[10:11]
	v_add_u32_e32 v0, v171, v228
	ds_read_u16 v238, v0
	ds_read_u16 v242, v0 offset:272
	ds_read_u16 v239, v0 offset:544
	ds_read_u16 v243, v0 offset:816
	ds_read_u16 v240, v0 offset:1088
	ds_read_u16 v244, v0 offset:1360
	ds_read_u16 v241, v0 offset:1632
	ds_read_u16 v245, v0 offset:1904
	s_waitcnt lgkmcnt(11)
	v_mfma_f32_16x16x32_bf16 v[140:143], v[4:7], v[148:151], v[140:143]
	s_waitcnt lgkmcnt(9)
	v_mfma_f32_16x16x32_bf16 v[144:147], v[12:15], v[156:159], v[144:147]
	v_mfma_f32_16x16x32_bf16 v[140:143], v[8:11], v[152:155], v[140:143]
	s_waitcnt lgkmcnt(8)
	v_mfma_f32_16x16x32_bf16 v[144:147], v[16:19], v[160:163], v[144:147]
	s_waitcnt lgkmcnt(4)
	v_perm_b32 v239, v243, v239, s8
	v_perm_b32 v238, v242, v238, s8
	s_waitcnt lgkmcnt(2)
	v_perm_b32 v240, v244, v240, s8
	s_waitcnt lgkmcnt(0)
	v_perm_b32 v241, v245, v241, s8
	s_cmp_eq_u64 s[38:39], 0
	s_cbranch_scc0 .Lrnn_w0
	s_waitcnt vmcnt(5)
	s_branch .Lrnn_wd
.Lrnn_w0:
	s_waitcnt vmcnt(6)
.Lrnn_wd:
	ds_write_b16 v175, v120
	ds_write_b16_d16_hi v175, v120 offset:272
	v_add_u32_e32 v120, v200, v228
	ds_write_b16 v120, v121 offset:544
	ds_write_b16_d16_hi v201, v121 offset:272
	ds_write_b16 v120, v122 offset:1088
	ds_write_b16_d16_hi v202, v122 offset:272
	ds_write_b16 v120, v123 offset:1632
	ds_write_b16_d16_hi v203, v123 offset:272
	v_add_u32_e32 v120, s6, v168
	v_ashrrev_i32_e32 v121, 31, v120
	v_lshlrev_b64 v[120:121], 11, v[120:121]
	v_lshl_add_u64 v[120:121], v[2:3], 0, v[120:121]
	global_load_dwordx4 v[120:123], v[120:121], off
	global_store_dwordx4 v[182:183], v[238:241], off
	v_cvt_pk_bf16_f32 v140, v140, v141
	v_cvt_pk_bf16_f32 v141, v142, v143
	v_cvt_pk_bf16_f32 v142, v144, v145
	v_cvt_pk_bf16_f32 v143, v146, v147
	v_cndmask_b32_e32 v184, 0, v142, vcc
	v_cndmask_b32_e32 v185, 0, v143, vcc
	v_mfma_f32_16x16x32_bf16 v[144:147], v[52:55], v[140:143], 0
	v_cndmask_b32_e32 v229, 0, v140, vcc
	v_cndmask_b32_e32 v230, 0, v141, vcc
	v_mfma_f32_16x16x32_bf16 v[148:151], v[68:71], v[140:143], 0
	v_mfma_f32_16x16x32_bf16 v[152:155], v[84:87], v[140:143], 0
	v_mfma_f32_16x16x32_bf16 v[156:159], v[100:103], v[140:143], 0
	ds_read_b128 v[140:143], v204 offset:128
	ds_read_b128 v[160:163], v205 offset:64
	ds_read_b128 v[164:167], v205 offset:80
	ds_read_b128 v[190:193], v204 offset:192
	ds_read_b128 v[238:241], v205 offset:96
	ds_read_b128 v[242:245], v205 offset:112
	s_waitcnt lgkmcnt(4)
	v_mfma_f32_16x16x32_bf16 v[140:143], v[20:23], v[160:163], v[140:143]
	s_waitcnt lgkmcnt(1)
	v_mfma_f32_16x16x32_bf16 v[160:163], v[28:31], v[238:241], v[190:193]
	v_mfma_f32_16x16x32_bf16 v[140:143], v[24:27], v[164:167], v[140:143]
	s_waitcnt lgkmcnt(0)
	v_mfma_f32_16x16x32_bf16 v[160:163], v[32:35], v[242:245], v[160:163]
	s_nop 5
	v_cvt_pk_bf16_f32 v140, v140, v141
	v_cvt_pk_bf16_f32 v141, v142, v143
	v_cvt_pk_bf16_f32 v142, v160, v161
	v_cvt_pk_bf16_f32 v143, v162, v163
	v_cndmask_b32_e64 v185, v185, v143, s[40:41]
	v_cndmask_b32_e64 v184, v184, v142, s[40:41]
	v_mfma_f32_16x16x32_bf16 v[144:147], v[56:59], v[140:143], v[144:147]
	v_cndmask_b32_e64 v230, v230, v141, s[40:41]
	v_cndmask_b32_e64 v229, v229, v140, s[40:41]
	v_mfma_f32_16x16x32_bf16 v[148:151], v[72:75], v[140:143], v[148:151]
	v_mfma_f32_16x16x32_bf16 v[152:155], v[88:91], v[140:143], v[152:155]
	v_mfma_f32_16x16x32_bf16 v[156:159], v[104:107], v[140:143], v[156:159]
	ds_read_b128 v[140:143], v204 offset:256
	ds_read_b128 v[160:163], v205 offset:128
	ds_read_b128 v[164:167], v205 offset:144
	ds_read_b128 v[190:193], v204 offset:320
	ds_read_b128 v[238:241], v205 offset:160
	ds_read_b128 v[242:245], v205 offset:176
	s_waitcnt lgkmcnt(4)
	v_mfma_f32_16x16x32_bf16 v[140:143], v[36:39], v[160:163], v[140:143]
	s_waitcnt lgkmcnt(1)
	v_mfma_f32_16x16x32_bf16 v[160:163], v[44:47], v[238:241], v[190:193]
	v_mfma_f32_16x16x32_bf16 v[140:143], v[40:43], v[164:167], v[140:143]
	s_waitcnt lgkmcnt(0)
	v_mfma_f32_16x16x32_bf16 v[160:163], v[48:51], v[242:245], v[160:163]
	s_nop 5
	v_cvt_pk_bf16_f32 v140, v140, v141
	v_cvt_pk_bf16_f32 v141, v142, v143
	v_cvt_pk_bf16_f32 v142, v160, v161
	v_cvt_pk_bf16_f32 v143, v162, v163
	v_cndmask_b32_e64 v231, v184, v142, s[42:43]
	v_cndmask_b32_e64 v184, v185, v143, s[42:43]
	v_mfma_f32_16x16x32_bf16 v[144:147], v[60:63], v[140:143], v[144:147]
	v_cndmask_b32_e64 v229, v229, v140, s[42:43]
	v_cndmask_b32_e64 v230, v230, v141, s[42:43]
	v_mfma_f32_16x16x32_bf16 v[148:151], v[76:79], v[140:143], v[148:151]
	v_mfma_f32_16x16x32_bf16 v[152:155], v[92:95], v[140:143], v[152:155]
	v_mfma_f32_16x16x32_bf16 v[160:163], v[108:111], v[140:143], v[156:159]
	ds_read_b128 v[140:143], v204 offset:384
	s_nop 1
	ds_read_b128 v[156:159], v205 offset:192
	ds_read_b128 v[164:167], v205 offset:208
	ds_read_b128 v[190:193], v204 offset:448
	ds_read_b128 v[238:241], v205 offset:224
	ds_read_b128 v[242:245], v205 offset:240
	ds_read_b128 v[246:249], v206
	s_waitcnt lgkmcnt(0)
	v_mfma_f32_16x16x32_bf16 v[140:143], v[246:249], v[156:159], v[140:143]
	ds_read_b128 v[156:159], v207
	s_waitcnt lgkmcnt(0)
	v_mfma_f32_16x16x32_bf16 v[156:159], v[156:159], v[238:241], v[190:193]
	s_nop 2
	ds_read_b128 v[190:193], v208
	s_waitcnt lgkmcnt(0)
	v_mfma_f32_16x16x32_bf16 v[140:143], v[190:193], v[164:167], v[140:143]
	ds_read_b128 v[164:167], v209
	s_waitcnt lgkmcnt(0)
	v_mfma_f32_16x16x32_bf16 v[156:159], v[164:167], v[242:245], v[156:159]
	s_nop 4
	v_cvt_pk_bf16_f32 v164, v140, v141
	v_cvt_pk_bf16_f32 v165, v142, v143
	s_nop 0
	v_cvt_pk_bf16_f32 v166, v156, v157
	v_cvt_pk_bf16_f32 v167, v158, v159
	v_cndmask_b32_e64 v184, v184, v167, s[44:45]
	v_cndmask_b32_e64 v185, v231, v166, s[44:45]
	v_mfma_f32_16x16x32_bf16 v[156:159], v[64:67], v[164:167], v[144:147]
	v_mfma_f32_16x16x32_bf16 v[144:147], v[80:83], v[164:167], v[148:151]
	v_mfma_f32_16x16x32_bf16 v[148:151], v[96:99], v[164:167], v[152:155]
	s_nop 2
	v_cndmask_b32_e64 v152, v230, v165, s[44:45]
	v_cndmask_b32_e64 v153, v229, v164, s[44:45]
	v_mfma_f32_16x16x32_bf16 v[140:143], v[112:115], v[164:167], v[160:163]
	v_lshlrev_b32_e32 v232, 16, v153
	v_and_b32_e32 v231, 0xffff0000, v153
	v_lshlrev_b32_e32 v230, 16, v152
	v_and_b32_e32 v229, 0xffff0000, v152
	ds_read_b128 v[160:163], v210
	ds_read_b128 v[152:155], v211
	ds_read_b128 v[164:167], v212
	s_waitcnt lgkmcnt(2)
	v_add_f32_e32 v156, v156, v160
	v_exp_f32_e32 v156, v156
	s_waitcnt lgkmcnt(1)
	v_add_f32_e32 v148, v148, v152
	v_exp_f32_e32 v148, v148
	v_add_f32_e32 v149, v149, v153
	v_add_f32_e32 v156, 1.0, v156
	v_rcp_f32_e64 v152, -v156
	v_add_f32_e32 v148, 1.0, v148
	v_rcp_f32_e32 v148, v148
	v_exp_f32_e32 v149, v149
	s_waitcnt lgkmcnt(0)
	v_mul_f32_e32 v152, v164, v152
	v_exp_f32_e32 v190, v152
	v_mul_f32_e32 v148, v148, v232
	v_add_f32_e32 v149, 1.0, v149
	v_rcp_f32_e32 v149, v149
	v_fma_f32 v152, -v190, v190, 1.0
	v_max_f32_e32 v152, 0, v152
	v_sqrt_f32_e32 v152, v152
	v_mul_f32_e32 v149, v149, v231
	v_and_b32_e32 v164, 0xffff0000, v184
	v_mul_f32_e32 v191, v148, v152
	v_add_f32_e32 v148, v157, v161
	v_exp_f32_e32 v148, v148
	ds_write_b64 v213, v[190:191]
	v_lshlrev_b32_e32 v161, 16, v185
	v_add_f32_e32 v148, 1.0, v148
	v_rcp_f32_e64 v148, -v148
	s_nop 0
	v_mul_f32_e32 v148, v165, v148
	v_exp_f32_e32 v148, v148
	s_nop 0
	v_fma_f32 v152, -v148, v148, 1.0
	v_max_f32_e32 v152, 0, v152
	v_sqrt_f32_e32 v152, v152
	s_nop 0
	v_mul_f32_e32 v149, v149, v152
	ds_write_b64 v214, v[148:149]
	v_add_f32_e32 v148, v158, v162
	v_exp_f32_e32 v148, v148
	v_add_f32_e32 v149, v150, v154
	v_exp_f32_e32 v149, v149
	v_and_b32_e32 v162, 0xffff0000, v185
	v_add_f32_e32 v148, 1.0, v148
	v_rcp_f32_e64 v148, -v148
	v_add_f32_e32 v149, 1.0, v149
	v_rcp_f32_e32 v149, v149
	v_mul_f32_e32 v148, v166, v148
	v_exp_f32_e32 v148, v148
	v_mul_f32_e32 v149, v149, v230
	v_fma_f32 v150, -v148, v148, 1.0
	v_max_f32_e32 v150, 0, v150
	v_sqrt_f32_e32 v150, v150
	s_nop 0
	v_mul_f32_e32 v149, v149, v150
	ds_write_b64 v215, v[148:149]
	v_add_f32_e32 v148, v159, v163
	v_exp_f32_e32 v148, v148
	v_add_f32_e32 v149, v151, v155
	v_exp_f32_e32 v149, v149
	v_lshlrev_b32_e32 v163, 16, v184
	v_add_f32_e32 v148, 1.0, v148
	v_rcp_f32_e64 v148, -v148
	v_add_f32_e32 v149, 1.0, v149
	v_rcp_f32_e32 v149, v149
	v_mul_f32_e32 v148, v167, v148
	v_exp_f32_e32 v148, v148
	v_mul_f32_e32 v149, v149, v229
	v_fma_f32 v150, -v148, v148, 1.0
	v_max_f32_e32 v150, 0, v150
	v_sqrt_f32_e32 v150, v150
	s_nop 0
	v_mul_f32_e32 v149, v149, v150
	ds_write_b64 v216, v[148:149]
	ds_read_b128 v[156:159], v217
	ds_read_b128 v[152:155], v218
	ds_read_b128 v[148:151], v219
	s_waitcnt lgkmcnt(2)
	v_add_f32_e32 v144, v144, v156
	v_exp_f32_e32 v144, v144
	s_waitcnt lgkmcnt(1)
	v_add_f32_e32 v140, v140, v152
	v_exp_f32_e32 v140, v140
	v_add_f32_e32 v141, v141, v153
	v_add_f32_e32 v144, 1.0, v144
	v_rcp_f32_e64 v144, -v144
	v_add_f32_e32 v140, 1.0, v140
	v_rcp_f32_e32 v140, v140
	v_exp_f32_e32 v141, v141
	s_waitcnt lgkmcnt(0)
	v_mul_f32_e32 v144, v148, v144
	v_exp_f32_e32 v160, v144
	v_mul_f32_e32 v140, v140, v161
	v_add_f32_e32 v141, 1.0, v141
	v_rcp_f32_e32 v141, v141
	v_fma_f32 v144, -v160, v160, 1.0
	v_max_f32_e32 v144, 0, v144
	v_sqrt_f32_e32 v144, v144
	v_mul_f32_e32 v141, v141, v162
	v_mul_f32_e32 v161, v140, v144
	v_add_f32_e32 v140, v145, v157
	v_exp_f32_e32 v140, v140
	ds_write_b64 v220, v[160:161]
	v_mov_b32_e32 v161, 0
	v_add_f32_e32 v140, 1.0, v140
	v_rcp_f32_e64 v140, -v140
	s_nop 0
	v_mul_f32_e32 v140, v149, v140
	v_exp_f32_e32 v140, v140
	s_nop 0
	v_fma_f32 v144, -v140, v140, 1.0
	v_max_f32_e32 v144, 0, v144
	v_sqrt_f32_e32 v144, v144
	s_nop 0
	v_mul_f32_e32 v141, v141, v144
	ds_write_b64 v221, v[140:141]
	v_add_f32_e32 v140, v146, v158
	v_exp_f32_e32 v140, v140
	v_add_f32_e32 v141, v142, v154
	v_exp_f32_e32 v141, v141
	v_add_f32_e32 v140, 1.0, v140
	v_rcp_f32_e64 v140, -v140
	v_add_f32_e32 v141, 1.0, v141
	v_rcp_f32_e32 v141, v141
	v_mul_f32_e32 v140, v150, v140
	v_exp_f32_e32 v140, v140
	v_mul_f32_e32 v141, v141, v163
	v_fma_f32 v142, -v140, v140, 1.0
	v_max_f32_e32 v142, 0, v142
	v_sqrt_f32_e32 v142, v142
	s_nop 0
	v_mul_f32_e32 v141, v141, v142
	ds_write_b64 v222, v[140:141]
	v_add_f32_e32 v140, v147, v159
	v_exp_f32_e32 v140, v140
	v_add_f32_e32 v141, v143, v155
	v_exp_f32_e32 v141, v141
	v_add_f32_e32 v140, 1.0, v140
	v_rcp_f32_e64 v140, -v140
	v_add_f32_e32 v141, 1.0, v141
	v_rcp_f32_e32 v141, v141
	v_mul_f32_e32 v140, v151, v140
	v_exp_f32_e32 v140, v140
	v_mul_f32_e32 v141, v141, v164
	v_fma_f32 v142, -v140, v140, 1.0
	v_max_f32_e32 v142, 0, v142
	v_sqrt_f32_e32 v142, v142
	s_nop 0
	v_mul_f32_e32 v141, v141, v142
	ds_write_b64 v223, v[140:141]
	s_waitcnt lgkmcnt(0)
	s_barrier
	ds_read_b128 v[148:151], v224
	ds_read_b128 v[152:155], v224 offset:16
	ds_read_b128 v[144:147], v224 offset:32
	ds_read_b128 v[140:143], v224 offset:48
	s_waitcnt lgkmcnt(3)
	v_fma_f32 v149, 0, v148, v149
	v_fma_f32 v156, v150, v149, v151
	v_mul_f32_e32 v157, v148, v150
	s_waitcnt lgkmcnt(2)
	v_fma_f32 v158, v152, v156, v153
	v_mul_f32_e32 v159, v157, v152
	v_mul_f32_e32 v160, v154, v159
	v_fmac_f32_e32 v155, v154, v158
	s_waitcnt lgkmcnt(1)
	v_fma_f32 v145, v144, v155, v145
	v_mul_f32_e32 v144, v144, v160
	v_mul_f32_e32 v154, v146, v144
	v_fmac_f32_e32 v147, v146, v145
	s_waitcnt lgkmcnt(0)
	v_fma_f32 v141, v140, v147, v141
	v_mul_f32_e32 v140, v140, v154
	v_mul_f32_e32 v146, v142, v140
	v_fmac_f32_e32 v143, v142, v141
	v_mov_b32_e32 v142, 1.0
	v_mov_b32_e32 v150, 0
	v_mov_b32_e32 v151, 1.0
	v_mov_b32_dpp v142, v146 row_shr:1 row_mask:0xf bank_mask:0xf
	v_mov_b32_dpp v150, v143 row_shr:1 row_mask:0xf bank_mask:0xf
	v_fma_f32 v150, v146, v150, v143
	v_mul_f32_e32 v142, v146, v142
	v_mov_b32_e32 v152, 0
	s_nop 0
	v_mov_b32_dpp v151, v142 row_shr:2 row_mask:0xf bank_mask:0xf
	v_mov_b32_dpp v152, v150 row_shr:2 row_mask:0xf bank_mask:0xf
	v_fmac_f32_e32 v150, v142, v152
	v_mul_f32_e32 v142, v142, v151
	v_mov_b32_e32 v151, 1.0
	v_mov_b32_e32 v152, 0
	s_nop 0
	v_mov_b32_dpp v151, v142 row_shr:4 row_mask:0xf bank_mask:0xf
	v_mov_b32_dpp v152, v150 row_shr:4 row_mask:0xf bank_mask:0xf
	v_fmac_f32_e32 v150, v142, v152
	v_mul_f32_e32 v142, v142, v151
	v_mov_b32_e32 v151, 1.0
	v_mov_b32_e32 v152, 0
	s_nop 0
	v_mov_b32_dpp v151, v142 row_shr:8 row_mask:0xf bank_mask:0xf
	v_mov_b32_dpp v152, v150 row_shr:8 row_mask:0xf bank_mask:0xf
	v_fmac_f32_e32 v150, v142, v152
	v_mul_f32_e32 v142, v142, v151
	v_mov_b32_e32 v151, 1.0
	v_mov_b32_dpp v161, v150 row_shr:1 row_mask:0xf bank_mask:0xf
	v_fmac_f32_e32 v150, v142, v225
	v_mov_b32_dpp v151, v142 row_shr:1 row_mask:0xf bank_mask:0xf
	v_fmac_f32_e32 v161, v151, v225
	ds_bpermute_b32 v225, v196, v150
	ds_read_b128 v[150:153], v226
	v_fmac_f32_e32 v145, v144, v161
	v_fmac_f32_e32 v149, v148, v161
	v_fmac_f32_e32 v147, v154, v161
	v_fmac_f32_e32 v141, v140, v161
	s_waitcnt lgkmcnt(0)
	v_lshlrev_b32_e32 v163, 16, v152
	v_lshlrev_b32_e32 v142, 16, v150
	v_mul_f32_e32 v144, v145, v163
	v_mul_f32_e32 v145, 0xbfb8aa3b, v163
	v_mul_f32_e32 v148, v149, v142
	v_mul_f32_e32 v142, 0xbfb8aa3b, v142
	v_exp_f32_e32 v145, v145
	v_exp_f32_e32 v142, v142
	v_and_b32_e32 v150, 0xffff0000, v150
	v_and_b32_e32 v152, 0xffff0000, v152
	v_add_f32_e32 v145, 1.0, v145
	v_add_f32_e32 v142, 1.0, v142
	v_rcp_f32_e32 v145, v145
	v_rcp_f32_e32 v142, v142
	v_lshlrev_b32_e32 v164, 16, v153
	v_lshlrev_b32_e32 v162, 16, v151
	v_fmac_f32_e32 v156, v157, v161
	v_mul_f32_e32 v149, 0xbfb8aa3b, v150
	v_mul_f32_e32 v144, v144, v145
	v_mul_f32_e32 v145, v147, v152
	v_mul_f32_e32 v147, 0xbfb8aa3b, v152
	v_mul_f32_e32 v140, v141, v164
	v_mul_f32_e32 v141, 0xbfb8aa3b, v164
	v_mul_f32_e32 v142, v148, v142
	v_mul_f32_e32 v148, v156, v150
	v_exp_f32_e32 v149, v149
	v_mul_f32_e32 v150, 0xbfb8aa3b, v162
	v_exp_f32_e32 v147, v147
	v_exp_f32_e32 v141, v141
	v_exp_f32_e32 v150, v150
	v_add_f32_e32 v149, 1.0, v149
	v_add_f32_e32 v147, 1.0, v147
	v_add_f32_e32 v141, 1.0, v141
	v_rcp_f32_e32 v149, v149
	v_add_f32_e32 v150, 1.0, v150
	v_rcp_f32_e32 v147, v147
	v_rcp_f32_e32 v141, v141
	v_rcp_f32_e32 v150, v150
	v_and_b32_e32 v153, 0xffff0000, v153
	v_fmac_f32_e32 v158, v159, v161
	v_and_b32_e32 v151, 0xffff0000, v151
	v_mul_f32_e32 v148, v148, v149
	v_mul_f32_e32 v149, v158, v162
	v_fmac_f32_e32 v155, v160, v161
	v_mul_f32_e32 v145, v145, v147
	v_mul_f32_e32 v147, v140, v141
	v_mul_f32_e32 v141, 0xbfb8aa3b, v153
	v_mul_f32_e32 v149, v149, v150
	v_mul_f32_e32 v150, v155, v151
	v_mul_f32_e32 v151, 0xbfb8aa3b, v151
	v_exp_f32_e32 v141, v141
	v_exp_f32_e32 v151, v151
	v_fmac_f32_e32 v143, v146, v161
	v_mul_f32_e32 v140, v143, v153
	v_add_f32_e32 v141, 1.0, v141
	v_add_f32_e32 v151, 1.0, v151
	v_rcp_f32_e32 v141, v141
	v_rcp_f32_e32 v151, v151
	v_mul_f32_e32 v143, v140, v141
	v_mul_f32_e32 v150, v150, v151
	v_cvt_pk_bf16_f32 v140, v142, v148
	v_cvt_pk_bf16_f32 v141, v149, v150
	v_cvt_pk_bf16_f32 v142, v144, v145
	v_cvt_pk_bf16_f32 v143, v147, v143
	ds_write_b128 v227, v[140:143]
	s_waitcnt vmcnt(5)
	ds_write_b128 v177, v[124:127] offset:816
	s_waitcnt vmcnt(4)
	ds_write_b128 v179, v[128:131] offset:816
	s_waitcnt vmcnt(3)
	ds_write_b128 v181, v[132:135] offset:816
	s_waitcnt vmcnt(2)
	ds_write_b128 v199, v[136:139] offset:816
	s_and_saveexec_b64 s[10:11], s[38:39]
	s_cbranch_execz .Lrnn_halo_done
	ds_write_b128 v177, v[116:119]
.Lrnn_halo_done:
	s_or_b64 exec, exec, s[10:11]
	s_branch .LBB0_112
